# full-grid barriers: waiting workgroups poll the TOP arrival counter itself (TOP >= (gen+1)*nx) instead of a generation word
# baseline (speedup 1.0000x reference)
; __device__ __forceinline__ unsigned xb_ld(unsigned* p)              { return __hip_atomic_load(p, __ATOMIC_RELAXED, __HIP_MEMORY_SCOPE_AGENT); }
; __device__ __forceinline__ unsigned xb_add(unsigned* p, unsigned v) { return __hip_atomic_fetch_add(p, v, __ATOMIC_RELAXED, __HIP_MEMORY_SCOPE_AGENT); }
; #define XB_SPIN(cond, bar) do { unsigned _sp = 0; while (cond) { __builtin_amdgcn_s_sleep(1); \
;     if ((++_sp & 255u) == 0u) { if (xb_ld(&(bar)[XB_TMO])) break; if (_sp > XB_SPIN_CAP) { atomicAdd(&(bar)[XB_TMO], 1u); break; } } } } while (0)
; __device__ __forceinline__ void xcd_barrier(const XcdBarrier& b) {
;     ...
;         const unsigned old = xb_add(&bar[XB_XSUB(b.x)], 1u);
;         const unsigned gen = old / nloc;
;         if (old + 1u == (gen + 1u) * nloc) {
;             __builtin_amdgcn_fence(__ATOMIC_RELEASE, "agent");
;             asm volatile("s_waitcnt vmcnt(0)" ::: "memory");
;             const unsigned og = xb_add(&bar[XB_TOP], 1u);
;             const unsigned tg = og / nx;
;             if (og + 1u == (tg + 1u) * nx) xb_add(&bar[XB_TOPGEN], 1u);
;             else XB_SPIN(xb_ld(&bar[XB_TOPGEN]) == tg, bar);
.LBB0_120:
	s_or_b64 exec, exec, s[38:39]
	v_cvt_f32_u32_e32 v4, v2
	s_waitcnt vmcnt(0)
	v_readfirstlane_b32 s8, v3
	v_sub_u32_e32 v3, 0, v2
	v_rcp_iflag_f32_e32 v4, v4
	v_add_u32_e32 v5, s8, v1
	v_mul_f32_e32 v4, 0x4f7ffffe, v4
	v_cvt_u32_f32_e32 v4, v4
	v_mul_lo_u32 v1, v3, v4
	v_mul_hi_u32 v1, v4, v1
	v_add_u32_e32 v1, v4, v1
	v_mul_hi_u32 v1, v5, v1
	v_mul_lo_u32 v3, v1, v2
	v_sub_u32_e32 v3, v5, v3
	v_add_u32_e32 v4, 1, v1
	v_cmp_ge_u32_e32 vcc, v3, v2
	s_nop 1
	v_cndmask_b32_e32 v1, v1, v4, vcc
	v_sub_u32_e32 v4, v3, v2
	v_cndmask_b32_e32 v3, v3, v4, vcc
	v_add_u32_e32 v4, 1, v1
	v_cmp_ge_u32_e32 vcc, v3, v2
	v_add_u32_e32 v3, 1, v5
	s_nop 0
	v_cndmask_b32_e32 v1, v1, v4, vcc
	v_mul_lo_u32 v4, v2, v1
	v_add_u32_e32 v2, v4, v2
	v_cmp_ne_u32_e32 vcc, v3, v2
	s_and_saveexec_b64 s[8:9], vcc
	s_xor_b64 s[8:9], exec, s[8:9]
	s_cbranch_execz .LBB0_134
	s_waitcnt lgkmcnt(0)
	v_add_u32_e32 v5, 1, v1
	v_mul_lo_u32 v5, v5, v0
	s_add_u32 s42, s34, 0x83400
	s_addc_u32 s43, s35, 0
	v_mov_b32_e32 v0, 0
	global_load_dword v0, v0, s[42:43] sc1
	s_waitcnt vmcnt(0)
	v_cmp_lt_u32_e32 vcc, v0, v5
	s_and_saveexec_b64 s[38:39], vcc
	s_cbranch_execz .LBB0_133
	s_add_u32 s40, s34, 0x80200
	s_addc_u32 s41, s35, 0
	s_mov_b32 s10, 1
	s_mov_b64 s[44:45], 0
	v_mov_b32_e32 v0, 0
	s_branch .LBB0_124

; __device__ __forceinline__ unsigned xb_ld(unsigned* p)              { return __hip_atomic_load(p, __ATOMIC_RELAXED, __HIP_MEMORY_SCOPE_AGENT); }
; #define XB_SPIN(cond, bar) do { unsigned _sp = 0; while (cond) { __builtin_amdgcn_s_sleep(1); \
;     if ((++_sp & 255u) == 0u) { if (xb_ld(&(bar)[XB_TMO])) break; if (_sp > XB_SPIN_CAP) { atomicAdd(&(bar)[XB_TMO], 1u); break; } } } } while (0)
; __device__ __forceinline__ void xcd_barrier(const XcdBarrier& b) {
;     ...
;             else XB_SPIN(xb_ld(&bar[XB_TOPGEN]) == tg, bar);
.LBB0_128:
	global_load_dword v2, v0, s[42:43] sc1
	s_add_i32 s10, s10, 1
	s_mov_b64 s[62:63], -1
	s_waitcnt vmcnt(0)
	v_cmp_ge_u32_e32 vcc, v2, v5
	s_orn2_b64 s[48:49], vcc, exec
	s_branch .LBB0_123

; __device__ __forceinline__ unsigned xb_ld(unsigned* p)              { return __hip_atomic_load(p, __ATOMIC_RELAXED, __HIP_MEMORY_SCOPE_AGENT); }
; __device__ __forceinline__ unsigned xb_add(unsigned* p, unsigned v) { return __hip_atomic_fetch_add(p, v, __ATOMIC_RELAXED, __HIP_MEMORY_SCOPE_AGENT); }
; #define XB_SPIN(cond, bar) do { unsigned _sp = 0; while (cond) { __builtin_amdgcn_s_sleep(1); \
;     if ((++_sp & 255u) == 0u) { if (xb_ld(&(bar)[XB_TMO])) break; if (_sp > XB_SPIN_CAP) { atomicAdd(&(bar)[XB_TMO], 1u); break; } } } } while (0)
; __device__ __forceinline__ void xcd_barrier(const XcdBarrier& b) {
;     ...
;         const unsigned old = xb_add(&bar[XB_XSUB(b.x)], 1u);
;         const unsigned gen = old / nloc;
;         if (old + 1u == (gen + 1u) * nloc) {
;             __builtin_amdgcn_fence(__ATOMIC_RELEASE, "agent");
;             asm volatile("s_waitcnt vmcnt(0)" ::: "memory");
;             const unsigned og = xb_add(&bar[XB_TOP], 1u);
;             const unsigned tg = og / nx;
;             if (og + 1u == (tg + 1u) * nx) xb_add(&bar[XB_TOPGEN], 1u);
;             else XB_SPIN(xb_ld(&bar[XB_TOPGEN]) == tg, bar);
.LBB0_367:
	s_or_b64 exec, exec, s[12:13]
	v_cvt_f32_u32_e32 v4, v2
	s_waitcnt vmcnt(0)
	v_readfirstlane_b32 s8, v3
	v_sub_u32_e32 v3, 0, v2
	v_rcp_iflag_f32_e32 v4, v4
	v_add_u32_e32 v5, s8, v1
	v_mul_f32_e32 v4, 0x4f7ffffe, v4
	v_cvt_u32_f32_e32 v4, v4
	v_mul_lo_u32 v1, v3, v4
	v_mul_hi_u32 v1, v4, v1
	v_add_u32_e32 v1, v4, v1
	v_mul_hi_u32 v1, v5, v1
	v_mul_lo_u32 v3, v1, v2
	v_sub_u32_e32 v3, v5, v3
	v_add_u32_e32 v4, 1, v1
	v_cmp_ge_u32_e32 vcc, v3, v2
	s_nop 1
	v_cndmask_b32_e32 v1, v1, v4, vcc
	v_sub_u32_e32 v4, v3, v2
	v_cndmask_b32_e32 v3, v3, v4, vcc
	v_add_u32_e32 v4, 1, v1
	v_cmp_ge_u32_e32 vcc, v3, v2
	v_add_u32_e32 v3, 1, v5
	s_nop 0
	v_cndmask_b32_e32 v1, v1, v4, vcc
	v_mul_lo_u32 v4, v2, v1
	v_add_u32_e32 v2, v4, v2
	v_cmp_ne_u32_e32 vcc, v3, v2
	s_and_saveexec_b64 s[8:9], vcc
	s_xor_b64 s[8:9], exec, s[8:9]
	s_cbranch_execz .LBB0_381
	s_waitcnt lgkmcnt(0)
	v_add_u32_e32 v5, 1, v1
	v_mul_lo_u32 v5, v5, v0
	s_add_u32 s16, s34, 0x83400
	s_addc_u32 s17, s35, 0
	v_mov_b32_e32 v0, 0
	global_load_dword v0, v0, s[16:17] sc1
	s_waitcnt vmcnt(0)
	v_cmp_lt_u32_e32 vcc, v0, v5
	s_and_saveexec_b64 s[12:13], vcc
	s_cbranch_execz .LBB0_380
	s_add_u32 s14, s34, 0x80200
	s_addc_u32 s15, s35, 0
	s_mov_b32 s10, 1
	s_mov_b64 s[20:21], 0
	v_mov_b32_e32 v0, 0
	s_branch .LBB0_371

; __device__ __forceinline__ unsigned xb_ld(unsigned* p)              { return __hip_atomic_load(p, __ATOMIC_RELAXED, __HIP_MEMORY_SCOPE_AGENT); }
; #define XB_SPIN(cond, bar) do { unsigned _sp = 0; while (cond) { __builtin_amdgcn_s_sleep(1); \
;     if ((++_sp & 255u) == 0u) { if (xb_ld(&(bar)[XB_TMO])) break; if (_sp > XB_SPIN_CAP) { atomicAdd(&(bar)[XB_TMO], 1u); break; } } } } while (0)
; __device__ __forceinline__ void xcd_barrier(const XcdBarrier& b) {
;     ...
;             else XB_SPIN(xb_ld(&bar[XB_TOPGEN]) == tg, bar);
.LBB0_375:
	global_load_dword v2, v0, s[16:17] sc1
	s_add_i32 s10, s10, 1
	s_mov_b64 s[40:41], -1
	s_waitcnt vmcnt(0)
	v_cmp_ge_u32_e32 vcc, v2, v5
	s_orn2_b64 s[38:39], vcc, exec
	s_branch .LBB0_370

; __device__ __forceinline__ unsigned xb_ld(unsigned* p)              { return __hip_atomic_load(p, __ATOMIC_RELAXED, __HIP_MEMORY_SCOPE_AGENT); }
; __device__ __forceinline__ unsigned xb_add(unsigned* p, unsigned v) { return __hip_atomic_fetch_add(p, v, __ATOMIC_RELAXED, __HIP_MEMORY_SCOPE_AGENT); }
; #define XB_SPIN(cond, bar) do { unsigned _sp = 0; while (cond) { __builtin_amdgcn_s_sleep(1); \
;     if ((++_sp & 255u) == 0u) { if (xb_ld(&(bar)[XB_TMO])) break; if (_sp > XB_SPIN_CAP) { atomicAdd(&(bar)[XB_TMO], 1u); break; } } } } while (0)
; __device__ __forceinline__ void xcd_barrier(const XcdBarrier& b) {
;     ...
;         const unsigned old = xb_add(&bar[XB_XSUB(b.x)], 1u);
;         const unsigned gen = old / nloc;
;         if (old + 1u == (gen + 1u) * nloc) {
;             __builtin_amdgcn_fence(__ATOMIC_RELEASE, "agent");
;             asm volatile("s_waitcnt vmcnt(0)" ::: "memory");
;             const unsigned og = xb_add(&bar[XB_TOP], 1u);
;             const unsigned tg = og / nx;
;             if (og + 1u == (tg + 1u) * nx) xb_add(&bar[XB_TOPGEN], 1u);
;             else XB_SPIN(xb_ld(&bar[XB_TOPGEN]) == tg, bar);
.LBB0_636:
	s_or_b64 exec, exec, s[16:17]
	v_cvt_f32_u32_e32 v4, v2
	s_waitcnt vmcnt(0)
	v_readfirstlane_b32 s10, v3
	v_sub_u32_e32 v3, 0, v2
	v_rcp_iflag_f32_e32 v4, v4
	v_add_u32_e32 v5, s10, v1
	v_mul_f32_e32 v4, 0x4f7ffffe, v4
	v_cvt_u32_f32_e32 v4, v4
	v_mul_lo_u32 v1, v3, v4
	v_mul_hi_u32 v1, v4, v1
	v_add_u32_e32 v1, v4, v1
	v_mul_hi_u32 v1, v5, v1
	v_mul_lo_u32 v3, v1, v2
	v_sub_u32_e32 v3, v5, v3
	v_add_u32_e32 v4, 1, v1
	v_cmp_ge_u32_e32 vcc, v3, v2
	s_nop 1
	v_cndmask_b32_e32 v1, v1, v4, vcc
	v_sub_u32_e32 v4, v3, v2
	v_cndmask_b32_e32 v3, v3, v4, vcc
	v_add_u32_e32 v4, 1, v1
	v_cmp_ge_u32_e32 vcc, v3, v2
	v_add_u32_e32 v3, 1, v5
	s_nop 0
	v_cndmask_b32_e32 v1, v1, v4, vcc
	v_mul_lo_u32 v4, v2, v1
	v_add_u32_e32 v2, v4, v2
	v_cmp_ne_u32_e32 vcc, v3, v2
	s_and_saveexec_b64 s[10:11], vcc
	s_xor_b64 s[12:13], exec, s[10:11]
	s_cbranch_execz .LBB0_650
	s_waitcnt lgkmcnt(0)
	v_add_u32_e32 v5, 1, v1
	v_mul_lo_u32 v5, v5, v0
	s_add_u32 s26, s34, 0x83400
	s_addc_u32 s27, s35, 0
	v_mov_b32_e32 v0, 0
	global_load_dword v0, v0, s[26:27] sc1
	s_waitcnt vmcnt(0)
	v_cmp_lt_u32_e32 vcc, v0, v5
	s_and_saveexec_b64 s[16:17], vcc
	s_cbranch_execz .LBB0_649
	s_add_u32 s20, s34, 0x80200
	s_addc_u32 s21, s35, 0
	s_mov_b32 s10, 1
	s_mov_b64 s[36:37], 0
	v_mov_b32_e32 v0, 0
	s_branch .LBB0_640

; __device__ __forceinline__ unsigned xb_ld(unsigned* p)              { return __hip_atomic_load(p, __ATOMIC_RELAXED, __HIP_MEMORY_SCOPE_AGENT); }
; #define XB_SPIN(cond, bar) do { unsigned _sp = 0; while (cond) { __builtin_amdgcn_s_sleep(1); \
;     if ((++_sp & 255u) == 0u) { if (xb_ld(&(bar)[XB_TMO])) break; if (_sp > XB_SPIN_CAP) { atomicAdd(&(bar)[XB_TMO], 1u); break; } } } } while (0)
; __device__ __forceinline__ void xcd_barrier(const XcdBarrier& b) {
;     ...
;             else XB_SPIN(xb_ld(&bar[XB_TOPGEN]) == tg, bar);
.LBB0_644:
	global_load_dword v2, v0, s[26:27] sc1
	s_add_i32 s10, s10, 1
	s_mov_b64 s[42:43], -1
	s_waitcnt vmcnt(0)
	v_cmp_ge_u32_e32 vcc, v2, v5
	s_orn2_b64 s[40:41], vcc, exec
	s_branch .LBB0_639

; __device__ __forceinline__ unsigned xb_ld(unsigned* p)              { return __hip_atomic_load(p, __ATOMIC_RELAXED, __HIP_MEMORY_SCOPE_AGENT); }
; __device__ __forceinline__ unsigned xb_add(unsigned* p, unsigned v) { return __hip_atomic_fetch_add(p, v, __ATOMIC_RELAXED, __HIP_MEMORY_SCOPE_AGENT); }
; #define XB_SPIN(cond, bar) do { unsigned _sp = 0; while (cond) { __builtin_amdgcn_s_sleep(1); \
;     if ((++_sp & 255u) == 0u) { if (xb_ld(&(bar)[XB_TMO])) break; if (_sp > XB_SPIN_CAP) { atomicAdd(&(bar)[XB_TMO], 1u); break; } } } } while (0)
; __device__ __forceinline__ void xcd_barrier(const XcdBarrier& b) {
;     ...
;         const unsigned old = xb_add(&bar[XB_XSUB(b.x)], 1u);
;         const unsigned gen = old / nloc;
;         if (old + 1u == (gen + 1u) * nloc) {
;             __builtin_amdgcn_fence(__ATOMIC_RELEASE, "agent");
;             asm volatile("s_waitcnt vmcnt(0)" ::: "memory");
;             const unsigned og = xb_add(&bar[XB_TOP], 1u);
;             const unsigned tg = og / nx;
;             if (og + 1u == (tg + 1u) * nx) xb_add(&bar[XB_TOPGEN], 1u);
;             else XB_SPIN(xb_ld(&bar[XB_TOPGEN]) == tg, bar);
.LBB0_716:
	s_or_b64 exec, exec, s[16:17]
	v_cvt_f32_u32_e32 v4, v2
	s_waitcnt vmcnt(0)
	v_readfirstlane_b32 s10, v3
	v_sub_u32_e32 v3, 0, v2
	v_rcp_iflag_f32_e32 v4, v4
	v_add_u32_e32 v5, s10, v1
	v_mul_f32_e32 v4, 0x4f7ffffe, v4
	v_cvt_u32_f32_e32 v4, v4
	v_mul_lo_u32 v1, v3, v4
	v_mul_hi_u32 v1, v4, v1
	v_add_u32_e32 v1, v4, v1
	v_mul_hi_u32 v1, v5, v1
	v_mul_lo_u32 v3, v1, v2
	v_sub_u32_e32 v3, v5, v3
	v_add_u32_e32 v4, 1, v1
	v_cmp_ge_u32_e32 vcc, v3, v2
	s_nop 1
	v_cndmask_b32_e32 v1, v1, v4, vcc
	v_sub_u32_e32 v4, v3, v2
	v_cndmask_b32_e32 v3, v3, v4, vcc
	v_add_u32_e32 v4, 1, v1
	v_cmp_ge_u32_e32 vcc, v3, v2
	v_add_u32_e32 v3, 1, v5
	s_nop 0
	v_cndmask_b32_e32 v1, v1, v4, vcc
	v_mul_lo_u32 v4, v2, v1
	v_add_u32_e32 v2, v4, v2
	v_cmp_ne_u32_e32 vcc, v3, v2
	s_and_saveexec_b64 s[10:11], vcc
	s_xor_b64 s[12:13], exec, s[10:11]
	s_cbranch_execz .LBB0_745
	s_waitcnt lgkmcnt(0)
	v_add_u32_e32 v5, 1, v1
	v_mul_lo_u32 v5, v5, v0
	s_add_u32 s20, s34, 0x83400
	s_addc_u32 s21, s35, 0
	v_mov_b32_e32 v0, 0
	global_load_dword v0, v0, s[20:21] sc1
	s_waitcnt vmcnt(0)
	v_cmp_lt_u32_e32 vcc, v0, v5
	s_and_saveexec_b64 s[16:17], vcc
	s_cbranch_execz .LBB0_744
	s_add_u32 s18, s34, 0x80200
	s_addc_u32 s19, s35, 0
	s_mov_b32 s10, 1
	s_mov_b64 s[26:27], 0
	v_mov_b32_e32 v0, 0
	s_branch .LBB0_720

; __device__ __forceinline__ unsigned xb_ld(unsigned* p)              { return __hip_atomic_load(p, __ATOMIC_RELAXED, __HIP_MEMORY_SCOPE_AGENT); }
; #define XB_SPIN(cond, bar) do { unsigned _sp = 0; while (cond) { __builtin_amdgcn_s_sleep(1); \
;     if ((++_sp & 255u) == 0u) { if (xb_ld(&(bar)[XB_TMO])) break; if (_sp > XB_SPIN_CAP) { atomicAdd(&(bar)[XB_TMO], 1u); break; } } } } while (0)
; __device__ __forceinline__ void xcd_barrier(const XcdBarrier& b) {
;     ...
;             else XB_SPIN(xb_ld(&bar[XB_TOPGEN]) == tg, bar);
.LBB0_724:
	global_load_dword v2, v0, s[20:21] sc1
	s_add_i32 s10, s10, 1
	s_mov_b64 s[40:41], -1
	s_waitcnt vmcnt(0)
	v_cmp_ge_u32_e32 vcc, v2, v5
	s_orn2_b64 s[38:39], vcc, exec
	s_branch .LBB0_719

; __device__ __forceinline__ unsigned xb_ld(unsigned* p)              { return __hip_atomic_load(p, __ATOMIC_RELAXED, __HIP_MEMORY_SCOPE_AGENT); }
; __device__ __forceinline__ unsigned xb_add(unsigned* p, unsigned v) { return __hip_atomic_fetch_add(p, v, __ATOMIC_RELAXED, __HIP_MEMORY_SCOPE_AGENT); }
; #define XB_SPIN(cond, bar) do { unsigned _sp = 0; while (cond) { __builtin_amdgcn_s_sleep(1); \
;     if ((++_sp & 255u) == 0u) { if (xb_ld(&(bar)[XB_TMO])) break; if (_sp > XB_SPIN_CAP) { atomicAdd(&(bar)[XB_TMO], 1u); break; } } } } while (0)
; __device__ __forceinline__ void xcd_barrier(const XcdBarrier& b) {
;     ...
;         const unsigned old = xb_add(&bar[XB_XSUB(b.x)], 1u);
;         const unsigned gen = old / nloc;
;         if (old + 1u == (gen + 1u) * nloc) {
;             __builtin_amdgcn_fence(__ATOMIC_RELEASE, "agent");
;             asm volatile("s_waitcnt vmcnt(0)" ::: "memory");
;             const unsigned og = xb_add(&bar[XB_TOP], 1u);
;             const unsigned tg = og / nx;
;             if (og + 1u == (tg + 1u) * nx) xb_add(&bar[XB_TOPGEN], 1u);
;             else XB_SPIN(xb_ld(&bar[XB_TOPGEN]) == tg, bar);
.LBB0_834:
	s_or_b64 exec, exec, s[12:13]
	v_cvt_f32_u32_e32 v4, v2
	s_waitcnt vmcnt(0)
	v_readfirstlane_b32 s8, v3
	v_sub_u32_e32 v3, 0, v2
	v_rcp_iflag_f32_e32 v4, v4
	v_add_u32_e32 v5, s8, v1
	v_mul_f32_e32 v4, 0x4f7ffffe, v4
	v_cvt_u32_f32_e32 v4, v4
	v_mul_lo_u32 v1, v3, v4
	v_mul_hi_u32 v1, v4, v1
	v_add_u32_e32 v1, v4, v1
	v_mul_hi_u32 v1, v5, v1
	v_mul_lo_u32 v3, v1, v2
	v_sub_u32_e32 v3, v5, v3
	v_add_u32_e32 v4, 1, v1
	v_cmp_ge_u32_e32 vcc, v3, v2
	s_nop 1
	v_cndmask_b32_e32 v1, v1, v4, vcc
	v_sub_u32_e32 v4, v3, v2
	v_cndmask_b32_e32 v3, v3, v4, vcc
	v_add_u32_e32 v4, 1, v1
	v_cmp_ge_u32_e32 vcc, v3, v2
	v_add_u32_e32 v3, 1, v5
	s_nop 0
	v_cndmask_b32_e32 v1, v1, v4, vcc
	v_mul_lo_u32 v4, v2, v1
	v_add_u32_e32 v2, v4, v2
	v_cmp_ne_u32_e32 vcc, v3, v2
	s_and_saveexec_b64 s[8:9], vcc
	s_xor_b64 s[8:9], exec, s[8:9]
	s_cbranch_execz .LBB0_848
	s_waitcnt lgkmcnt(0)
	v_add_u32_e32 v5, 1, v1
	v_mul_lo_u32 v5, v5, v0
	s_add_u32 s18, s34, 0x83400
	s_addc_u32 s19, s35, 0
	v_mov_b32_e32 v0, 0
	global_load_dword v0, v0, s[18:19] sc1
	s_waitcnt vmcnt(0)
	v_cmp_lt_u32_e32 vcc, v0, v5
	s_and_saveexec_b64 s[12:13], vcc
	s_cbranch_execz .LBB0_847
	s_add_u32 s16, s34, 0x80200
	s_addc_u32 s17, s35, 0
	s_mov_b32 s10, 1
	s_mov_b64 s[20:21], 0
	v_mov_b32_e32 v0, 0
	s_branch .LBB0_838

; __device__ __forceinline__ unsigned xb_ld(unsigned* p)              { return __hip_atomic_load(p, __ATOMIC_RELAXED, __HIP_MEMORY_SCOPE_AGENT); }
; #define XB_SPIN(cond, bar) do { unsigned _sp = 0; while (cond) { __builtin_amdgcn_s_sleep(1); \
;     if ((++_sp & 255u) == 0u) { if (xb_ld(&(bar)[XB_TMO])) break; if (_sp > XB_SPIN_CAP) { atomicAdd(&(bar)[XB_TMO], 1u); break; } } } } while (0)
; __device__ __forceinline__ void xcd_barrier(const XcdBarrier& b) {
;     ...
;             else XB_SPIN(xb_ld(&bar[XB_TOPGEN]) == tg, bar);
.LBB0_842:
	global_load_dword v2, v0, s[18:19] sc1
	s_add_i32 s10, s10, 1
	s_mov_b64 s[38:39], -1
	s_waitcnt vmcnt(0)
	v_cmp_ge_u32_e32 vcc, v2, v5
	s_orn2_b64 s[36:37], vcc, exec
	s_branch .LBB0_837

; __device__ __forceinline__ unsigned xb_ld(unsigned* p)              { return __hip_atomic_load(p, __ATOMIC_RELAXED, __HIP_MEMORY_SCOPE_AGENT); }
; #define XB_SPIN(cond, bar) do { unsigned _sp = 0; while (cond) { __builtin_amdgcn_s_sleep(1); \
;     if ((++_sp & 255u) == 0u) { if (xb_ld(&(bar)[XB_TMO])) break; if (_sp > XB_SPIN_CAP) { atomicAdd(&(bar)[XB_TMO], 1u); break; } } } } while (0)
; __device__ __forceinline__ void xcd_barrier(const XcdBarrier& b) {
;     ...
;             else XB_SPIN(xb_ld(&bar[XB_TOPGEN]) == tg, bar);
.LBB0_983:
	global_load_dword v2, v0, s[18:19] sc1
	s_add_i32 s10, s10, 1
	s_mov_b64 s[26:27], -1
	s_waitcnt vmcnt(0)
	v_cmp_ge_u32_e32 vcc, v2, v5
	s_orn2_b64 s[24:25], vcc, exec
	s_branch .LBB0_978

; __device__ __forceinline__ unsigned xb_ld(unsigned* p)              { return __hip_atomic_load(p, __ATOMIC_RELAXED, __HIP_MEMORY_SCOPE_AGENT); }
; __device__ __forceinline__ unsigned xb_add(unsigned* p, unsigned v) { return __hip_atomic_fetch_add(p, v, __ATOMIC_RELAXED, __HIP_MEMORY_SCOPE_AGENT); }
; #define XB_SPIN(cond, bar) do { unsigned _sp = 0; while (cond) { __builtin_amdgcn_s_sleep(1); \
;     if ((++_sp & 255u) == 0u) { if (xb_ld(&(bar)[XB_TMO])) break; if (_sp > XB_SPIN_CAP) { atomicAdd(&(bar)[XB_TMO], 1u); break; } } } } while (0)
; __device__ __forceinline__ void xcd_barrier(const XcdBarrier& b) {
;     ...
;         const unsigned old = xb_add(&bar[XB_XSUB(b.x)], 1u);
;         const unsigned gen = old / nloc;
;         if (old + 1u == (gen + 1u) * nloc) {
;             __builtin_amdgcn_fence(__ATOMIC_RELEASE, "agent");
;             asm volatile("s_waitcnt vmcnt(0)" ::: "memory");
;             const unsigned og = xb_add(&bar[XB_TOP], 1u);
;             const unsigned tg = og / nx;
;             if (og + 1u == (tg + 1u) * nx) xb_add(&bar[XB_TOPGEN], 1u);
;             else XB_SPIN(xb_ld(&bar[XB_TOPGEN]) == tg, bar);
.LBB0_1178:
	s_or_b64 exec, exec, s[8:9]
	v_cvt_f32_u32_e32 v4, v2
	s_waitcnt vmcnt(0)
	v_readfirstlane_b32 s6, v3
	v_sub_u32_e32 v3, 0, v2
	v_rcp_iflag_f32_e32 v4, v4
	v_add_u32_e32 v5, s6, v1
	v_mul_f32_e32 v4, 0x4f7ffffe, v4
	v_cvt_u32_f32_e32 v4, v4
	v_mul_lo_u32 v1, v3, v4
	v_mul_hi_u32 v1, v4, v1
	v_add_u32_e32 v1, v4, v1
	v_mul_hi_u32 v1, v5, v1
	v_mul_lo_u32 v3, v1, v2
	v_sub_u32_e32 v3, v5, v3
	v_add_u32_e32 v4, 1, v1
	v_cmp_ge_u32_e32 vcc, v3, v2
	s_nop 1
	v_cndmask_b32_e32 v1, v1, v4, vcc
	v_sub_u32_e32 v4, v3, v2
	v_cndmask_b32_e32 v3, v3, v4, vcc
	v_add_u32_e32 v4, 1, v1
	v_cmp_ge_u32_e32 vcc, v3, v2
	v_add_u32_e32 v3, 1, v5
	s_nop 0
	v_cndmask_b32_e32 v1, v1, v4, vcc
	v_mul_lo_u32 v4, v2, v1
	v_add_u32_e32 v2, v4, v2
	v_cmp_ne_u32_e32 vcc, v3, v2
	s_and_saveexec_b64 s[6:7], vcc
	s_xor_b64 s[6:7], exec, s[6:7]
	s_cbranch_execz .LBB0_1192
	s_waitcnt lgkmcnt(0)
	v_add_u32_e32 v5, 1, v1
	v_mul_lo_u32 v5, v5, v0
	s_add_u32 s12, s34, 0x83400
	s_addc_u32 s13, s35, 0
	v_mov_b32_e32 v0, 0
	global_load_dword v0, v0, s[12:13] sc1
	s_waitcnt vmcnt(0)
	v_cmp_lt_u32_e32 vcc, v0, v5
	s_and_saveexec_b64 s[8:9], vcc
	s_cbranch_execz .LBB0_1191
	s_add_u32 s10, s34, 0x80200
	s_addc_u32 s11, s35, 0
	s_mov_b32 s24, 1
	s_mov_b64 s[14:15], 0
	v_mov_b32_e32 v0, 0
	s_branch .LBB0_1182

; __device__ __forceinline__ unsigned xb_ld(unsigned* p)              { return __hip_atomic_load(p, __ATOMIC_RELAXED, __HIP_MEMORY_SCOPE_AGENT); }
; #define XB_SPIN(cond, bar) do { unsigned _sp = 0; while (cond) { __builtin_amdgcn_s_sleep(1); \
;     if ((++_sp & 255u) == 0u) { if (xb_ld(&(bar)[XB_TMO])) break; if (_sp > XB_SPIN_CAP) { atomicAdd(&(bar)[XB_TMO], 1u); break; } } } } while (0)
; __device__ __forceinline__ void xcd_barrier(const XcdBarrier& b) {
;     ...
;             else XB_SPIN(xb_ld(&bar[XB_TOPGEN]) == tg, bar);
.LBB0_1186:
	global_load_dword v2, v0, s[12:13] sc1
	s_add_i32 s24, s24, 1
	s_mov_b64 s[20:21], -1
	s_waitcnt vmcnt(0)
	v_cmp_ge_u32_e32 vcc, v2, v5
	s_orn2_b64 s[18:19], vcc, exec
	s_branch .LBB0_1181
